# RG-LRU fast paths: gate-GEMM LDS fragment reads issued ahead of the prefetch address math/loads
# baseline (speedup 1.0000x reference)
; #define MFMA16(a, b, c) __builtin_amdgcn_mfma_f32_16x16x32_bf16((a), (b), (c), 0, 0, 0)
; __device__ __forceinline__ void rglru_unit(const Params& p, const WS& ws, int j, int u, bool dry = false) {
;     ...
;   auto prefetch = [&](int tile, u32x4 (&xin)[4], bf16_t (&gav)[8]) {
;     const int t0 = 64 * tile;
; #pragma unroll
;     for (int i = 0; i < 4; ++i) {
;       const int ci = tid + 256 * i; const int row = ci >> 4, ch = ci & 15; const int t = t0 + row;
;       xin[i] = (u32x4){0, 0, 0, 0};
;       if (t < T_) xin[i] = *(const u32x4*)(ws.XA + (size_t)(b * T_ + t) * 1024 + 128 * g + 8 * ch);
;     }
; #pragma unroll
;     for (int i = 0; i < 8; ++i) {
;       const int t = t0 + 8 * ssg + i;
;       gav[i] = 0;
;       if (t < T_) gav[i] = ws.GA[(size_t)(b * T_ + t) * 1024 + 128 * g + 32 * jq + sc];
;     }
;   };
;     ...
;       for (int ks = 0; ks < 4; ++ks) {
;         const bf16x8 xf = *(const bf16x8*)(XC + (16 * w + lr) * 136 + 32 * ks + 8 * lq);
; #pragma unroll
;         for (int gate = 0; gate < 2; ++gate)
; #pragma unroll
;           for (int mt = 0; mt < 2; ++mt) {
;             const bf16x8 wf = *(const bf16x8*)(WG + (gate * 32 + 16 * mt + lr) * 136 + 32 * ks + 8 * lq);
;             ga_[gate][mt] = MFMA16(wf, xf, ga_[gate][mt]);
;           }
.LBB0_1394:
	s_add_i32 s13, s7, -1
	s_cmp_gt_u32 s13, 30
	v_mov_b32_e32 v133, v127
	v_mov_b32_e32 v134, v128
	v_mov_b32_e32 v131, v123
	v_mov_b32_e32 v132, v124
	v_mov_b32_e32 v129, v121
	v_mov_b32_e32 v130, v122
	v_mov_b32_e32 v125, v119
	v_mov_b32_e32 v126, v120
	s_cbranch_scc1 .LBB0_1420
	s_cmpk_gt_i32 s6, 0x750
	s_cbranch_scc1 .Lrg_pslow1
	ds_read_b128 v[52:55], v111
	ds_read_b128 v[56:59], v112 offset:17408
	ds_read_b128 v[60:63], v112 offset:21760
	ds_read_b128 v[64:67], v112 offset:26112
	ds_read_b128 v[136:139], v112 offset:30464
	ds_read_b128 v[212:215], v111 offset:64
	ds_read_b128 v[216:219], v111 offset:128
	ds_read_b128 v[220:223], v111 offset:192
	ds_read_b128 v[224:227], v112 offset:17472
	ds_read_b128 v[228:231], v112 offset:21824
	ds_read_b128 v[232:235], v112 offset:26176
	ds_read_b128 v[244:247], v112 offset:30528
	ds_read_b128 v[248:251], v112 offset:17536
	ds_read_b128 v[252:255], v112 offset:21888
	s_mov_b64 s[4:5], 0x1000
	s_mov_b64 s[52:53], 0x8000
	v_add_u32_e32 v14, s6, v118
	v_add_u32_e32 v14, 0x80, v14
	v_ashrrev_i32_e32 v15, 31, v14
	v_lshlrev_b64 v[14:15], 11, v[14:15]
	v_lshl_add_u64 v[14:15], v[76:77], 0, v[14:15]
	global_load_dwordx4 v[20:23], v[14:15], off
	v_lshl_add_u64 v[14:15], v[14:15], 0, s[52:53]
	global_load_dwordx4 v[24:27], v[14:15], off
	v_lshl_add_u64 v[14:15], v[14:15], 0, s[52:53]
	global_load_dwordx4 v[28:31], v[14:15], off
	v_lshl_add_u64 v[14:15], v[14:15], 0, s[52:53]
	global_load_dwordx4 v[32:35], v[14:15], off
	v_add_u32_e32 v14, s6, v69
	v_add_u32_e32 v14, 0x80, v14
	v_ashrrev_i32_e32 v15, 31, v14
	v_lshlrev_b64 v[14:15], 11, v[14:15]
	v_lshl_add_u64 v[14:15], v[74:75], 0, v[14:15]
	global_load_ushort v126, v[14:15], off
	global_load_ushort v125, v[14:15], off offset:2048
	v_lshl_add_u64 v[14:15], v[14:15], 0, s[4:5]
	global_load_ushort v130, v[14:15], off
	global_load_ushort v129, v[14:15], off offset:2048
	v_lshl_add_u64 v[14:15], v[14:15], 0, s[4:5]
	global_load_ushort v132, v[14:15], off
	global_load_ushort v131, v[14:15], off offset:2048
	v_lshl_add_u64 v[14:15], v[14:15], 0, s[4:5]
	global_load_ushort v134, v[14:15], off
	global_load_ushort v133, v[14:15], off offset:2048
	s_branch .Lrg_mm1

; __device__ __forceinline__ float bf2f(bf16_t v) { return __uint_as_float(((unsigned)v) << 16); }
; __device__ __forceinline__ float sigmoidf_(float x) { return __builtin_amdgcn_rcpf(1.f + __expf(-x)); }
; #define MFMA16(a, b, c) __builtin_amdgcn_mfma_f32_16x16x32_bf16((a), (b), (c), 0, 0, 0)
; __device__ __forceinline__ void rglru_unit(const Params& p, const WS& ws, int j, int u, bool dry = false) {
;     ...
;       for (int ks = 0; ks < 4; ++ks) {
;         const bf16x8 xf = *(const bf16x8*)(XC + (16 * w + lr) * 136 + 32 * ks + 8 * lq);
; #pragma unroll
;         for (int gate = 0; gate < 2; ++gate)
; #pragma unroll
;           for (int mt = 0; mt < 2; ++mt) {
;             const bf16x8 wf = *(const bf16x8*)(WG + (gate * 32 + 16 * mt + lr) * 136 + 32 * ks + 8 * lq);
;             ga_[gate][mt] = MFMA16(wf, xf, ga_[gate][mt]);
;           }
;       }
;       const int tok = 16 * w + lr;
; #pragma unroll
;       for (int mt = 0; mt < 2; ++mt)
; #pragma unroll
;         for (int jj = 0; jj < 4; ++jj) {
;           const int n = 16 * mt + 4 * lq + jj;
;           const float xcv = bf2f(XC[tok * 136 + 32 * jq + n]);
;           const float r = sigmoidf_(ga_[0][mt][jj] + ba[mt][jj]);
;           const float ig = sigmoidf_(ga_[1][mt][jj] + bx[mt][jj]);
;           const float la = -r * sp[mt][jj];
;           const float a = __expf(la);
;           const float x2 = 2.f * la;
;           const float om = x2 > -0.02f ? -x2 * (1.f + 0.5f * x2 * (1.f + x2 * (1.f / 3.f))) : 1.f - a * a;
;           const float mult = __builtin_amdgcn_sqrtf(fmaxf(om, 0.f));
;           AUa[tok * 33 + n] = a;
;           AUu[tok * 33 + n] = mult * ig * xcv;
;         }
.Lrg_mm1:
	s_waitcnt lgkmcnt(12)
	v_mfma_f32_16x16x32_bf16 v[56:59], v[56:59], v[52:55], 0
	s_waitcnt lgkmcnt(11)
	v_mfma_f32_16x16x32_bf16 v[60:63], v[60:63], v[52:55], 0
	s_waitcnt lgkmcnt(10)
	v_mfma_f32_16x16x32_bf16 v[64:67], v[64:67], v[52:55], 0
	s_waitcnt lgkmcnt(9)
	v_mfma_f32_16x16x32_bf16 v[52:55], v[136:139], v[52:55], 0
	s_nop 0
	s_nop 0
	s_waitcnt lgkmcnt(5)
	v_mfma_f32_16x16x32_bf16 v[56:59], v[224:227], v[212:215], v[56:59]
	ds_read_b128 v[224:227], v112 offset:26240
	s_nop 0
	s_waitcnt lgkmcnt(5)
	v_mfma_f32_16x16x32_bf16 v[60:63], v[228:231], v[212:215], v[60:63]
	ds_read_b128 v[228:231], v112 offset:30592
	s_nop 0
	s_waitcnt lgkmcnt(5)
	v_mfma_f32_16x16x32_bf16 v[64:67], v[232:235], v[212:215], v[64:67]
	ds_read_b128 v[232:235], v112 offset:17600
	s_nop 0
	s_waitcnt lgkmcnt(5)
	v_mfma_f32_16x16x32_bf16 v[52:55], v[244:247], v[212:215], v[52:55]
	ds_read_b128 v[244:247], v112 offset:21952
	s_nop 0
	s_nop 0
	s_waitcnt lgkmcnt(5)
	v_mfma_f32_16x16x32_bf16 v[56:59], v[248:251], v[216:219], v[56:59]
	ds_read_b128 v[248:251], v112 offset:26304
	s_nop 0
	s_waitcnt lgkmcnt(5)
	v_mfma_f32_16x16x32_bf16 v[60:63], v[252:255], v[216:219], v[60:63]
	ds_read_b128 v[252:255], v112 offset:30656
	s_nop 0
	s_waitcnt lgkmcnt(5)
	v_mfma_f32_16x16x32_bf16 v[140:143], v[224:227], v[216:219], v[64:67]
	s_nop 2
	s_nop 0
	s_waitcnt lgkmcnt(4)
	v_mfma_f32_16x16x32_bf16 v[52:55], v[228:231], v[216:219], v[52:55]
	s_nop 0
	s_nop 0
	ds_read_u16 v13, v113
	s_waitcnt lgkmcnt(4)
	v_mfma_f32_16x16x32_bf16 v[64:67], v[232:235], v[220:223], v[56:59]
	s_nop 2
	s_nop 0
	s_waitcnt lgkmcnt(3)
	v_mfma_f32_16x16x32_bf16 v[56:59], v[244:247], v[220:223], v[60:63]
	s_nop 2
	s_nop 0
	v_add_f32_e32 v14, v0, v64
	v_mul_f32_e32 v14, 0xbfb8aa3b, v14
	v_exp_f32_e32 v14, v14
	s_waitcnt lgkmcnt(2)
	v_mfma_f32_16x16x32_bf16 v[60:63], v[248:251], v[220:223], v[140:143]
	s_nop 2
	s_nop 0
	v_add_f32_e32 v14, 1.0, v14
	v_rcp_f32_e64 v14, -v14
	s_waitcnt lgkmcnt(0)
	v_mfma_f32_16x16x32_bf16 v[52:55], v[252:255], v[220:223], v[52:55]
	v_mul_f32_e32 v14, v89, v14
	v_mul_f32_e32 v15, 0x3fb8aa3b, v14
	v_exp_f32_e32 v15, v15
	v_add_f32_e32 v14, v14, v14
	v_cmp_nlt_f32_e64 s[52:53], s29, v14
	s_and_saveexec_b64 s[4:5], s[52:53]
	s_xor_b64 s[4:5], exec, s[4:5]
	v_fma_f32 v64, -v15, v15, 1.0
	s_andn2_saveexec_b64 s[4:5], s[4:5]
	v_pk_mul_f32 v[136:137], v[14:15], s[88:89] op_sel_hi:[0,1]
	v_add_f32_e32 v64, 1.0, v137
	v_fma_f32 v64, v136, v64, 1.0
	v_mul_f32_e64 v64, v64, -v14
	s_or_b64 exec, exec, s[4:5]
	v_add_f32_e32 v14, v8, v60
	v_max_f32_e32 v60, v64, v64
	v_add_f32_e32 v64, v1, v65
	v_mul_f32_e32 v14, 0xbfb8aa3b, v14
	v_mul_f32_e32 v64, 0xbfb8aa3b, v64
	v_exp_f32_e32 v14, v14
	v_exp_f32_e32 v64, v64
	v_max_f32_e32 v60, 0, v60
	v_sqrt_f32_e32 v60, v60
	v_add_f32_e32 v14, 1.0, v14
	v_add_f32_e32 v64, 1.0, v64
	v_rcp_f32_e32 v14, v14
	v_rcp_f32_e64 v64, -v64
	v_lshlrev_b32_e32 v13, 16, v13
	v_mul_f32_e32 v14, v14, v60
	v_mul_f32_e32 v64, v93, v64
	v_mul_f32_e32 v14, v14, v13
	ds_read_u16 v60, v113 offset:2
	v_mul_f32_e32 v13, 0x3fb8aa3b, v64
	v_exp_f32_e32 v13, v13
	ds_write2st64_b32 v72, v15, v14 offset0:136 offset1:169
	v_add_f32_e32 v14, v64, v64
	v_cmp_nlt_f32_e64 s[52:53], s29, v14
	s_and_saveexec_b64 s[4:5], s[52:53]
	s_xor_b64 s[4:5], exec, s[4:5]
	v_fma_f32 v15, -v13, v13, 1.0
	s_andn2_saveexec_b64 s[4:5], s[4:5]
	v_pk_mul_f32 v[64:65], v[14:15], s[88:89] op_sel_hi:[0,1]
	v_add_f32_e32 v15, 1.0, v65
	v_fma_f32 v15, v64, v15, 1.0
	v_mul_f32_e64 v15, v15, -v14
	s_or_b64 exec, exec, s[4:5]
	s_waitcnt lgkmcnt(1)
	v_lshlrev_b32_e32 v14, 16, v60
	v_add_f32_e32 v60, v9, v61
	v_mul_f32_e32 v60, 0xbfb8aa3b, v60
	v_exp_f32_e32 v60, v60
	v_max_f32_e32 v15, v15, v15
	v_max_f32_e32 v15, 0, v15
	v_sqrt_f32_e32 v15, v15
	v_add_f32_e32 v60, 1.0, v60
	v_rcp_f32_e32 v60, v60
	v_add_u32_e32 v135, 4, v72
	v_mul_f32_e32 v15, v60, v15
	v_mul_f32_e32 v14, v15, v14
	ds_write2st64_b32 v135, v13, v14 offset0:136 offset1:169
	v_add_f32_e32 v14, v2, v66
	v_mul_f32_e32 v14, 0xbfb8aa3b, v14
	v_exp_f32_e32 v14, v14
	ds_read_u16 v13, v113 offset:4
	v_add_f32_e32 v14, 1.0, v14
	v_rcp_f32_e64 v14, -v14
	s_nop 0
	v_mul_f32_e32 v14, v95, v14
	v_mul_f32_e32 v15, 0x3fb8aa3b, v14
	v_exp_f32_e32 v15, v15
	v_add_f32_e32 v14, v14, v14
	v_cmp_nlt_f32_e64 s[52:53], s29, v14
	s_and_saveexec_b64 s[4:5], s[52:53]
	s_xor_b64 s[4:5], exec, s[4:5]
	v_fma_f32 v60, -v15, v15, 1.0
	s_andn2_saveexec_b64 s[4:5], s[4:5]
	v_pk_mul_f32 v[60:61], v[14:15], s[88:89] op_sel_hi:[0,1]
	v_add_f32_e32 v61, 1.0, v61
	v_fma_f32 v60, v60, v61, 1.0
	v_mul_f32_e64 v60, v60, -v14
	s_or_b64 exec, exec, s[4:5]
	v_add_f32_e32 v14, v10, v62
	v_mul_f32_e32 v14, 0xbfb8aa3b, v14
	v_exp_f32_e32 v14, v14
	v_max_f32_e32 v60, v60, v60
	v_max_f32_e32 v60, 0, v60
	v_sqrt_f32_e32 v60, v60
	v_add_f32_e32 v14, 1.0, v14
	v_rcp_f32_e32 v14, v14
	s_waitcnt lgkmcnt(0)
	v_lshlrev_b32_e32 v13, 16, v13
	v_add_u32_e32 v136, 8, v72
	v_mul_f32_e32 v14, v14, v60
	v_mul_f32_e32 v13, v14, v13
	v_add_f32_e32 v14, v3, v67
	v_mul_f32_e32 v14, 0xbfb8aa3b, v14
	v_exp_f32_e32 v14, v14
	ds_write2st64_b32 v136, v15, v13 offset0:136 offset1:169
	ds_read_u16 v13, v113 offset:6
	v_add_f32_e32 v14, 1.0, v14
	v_rcp_f32_e64 v14, -v14
	s_nop 0
	v_mul_f32_e32 v14, v96, v14
	v_mul_f32_e32 v15, 0x3fb8aa3b, v14
	v_exp_f32_e32 v15, v15
	v_add_f32_e32 v14, v14, v14
	v_cmp_nlt_f32_e64 s[52:53], s29, v14
	s_and_saveexec_b64 s[4:5], s[52:53]
	s_xor_b64 s[4:5], exec, s[4:5]
	v_fma_f32 v60, -v15, v15, 1.0
	s_andn2_saveexec_b64 s[4:5], s[4:5]
	v_pk_mul_f32 v[60:61], v[14:15], s[88:89] op_sel_hi:[0,1]
	v_add_f32_e32 v61, 1.0, v61
	v_fma_f32 v60, v60, v61, 1.0
	v_mul_f32_e64 v60, v60, -v14
	s_or_b64 exec, exec, s[4:5]
	v_add_f32_e32 v14, v11, v63
	v_mul_f32_e32 v14, 0xbfb8aa3b, v14
	v_exp_f32_e32 v14, v14
	v_max_f32_e32 v60, v60, v60
	v_max_f32_e32 v60, 0, v60
	v_sqrt_f32_e32 v60, v60
	v_add_f32_e32 v14, 1.0, v14
	v_rcp_f32_e32 v14, v14
	s_waitcnt lgkmcnt(0)
; __device__ __forceinline__ float bf2f(bf16_t v) { return __uint_as_float(((unsigned)v) << 16); }
; __device__ __forceinline__ float sigmoidf_(float x) { return __builtin_amdgcn_rcpf(1.f + __expf(-x)); }
; __device__ __forceinline__ void rglru_unit(const Params& p, const WS& ws, int j, int u, bool dry = false) {
;     ...
; #pragma unroll
;       for (int mt = 0; mt < 2; ++mt)
; #pragma unroll
;         for (int jj = 0; jj < 4; ++jj) {
;           const int n = 16 * mt + 4 * lq + jj;
;           const float xcv = bf2f(XC[tok * 136 + 32 * jq + n]);
;           const float r = sigmoidf_(ga_[0][mt][jj] + ba[mt][jj]);
;           const float ig = sigmoidf_(ga_[1][mt][jj] + bx[mt][jj]);
;           const float la = -r * sp[mt][jj];
;           const float a = __expf(la);
;           const float x2 = 2.f * la;
;           const float om = x2 > -0.02f ? -x2 * (1.f + 0.5f * x2 * (1.f + x2 * (1.f / 3.f))) : 1.f - a * a;
;           const float mult = __builtin_amdgcn_sqrtf(fmaxf(om, 0.f));
;           AUa[tok * 33 + n] = a;
;           AUu[tok * 33 + n] = mult * ig * xcv;
;         }
;     }
;     __syncthreads();
;     {
;       float A = 1.f, Hh = 0.f;
; #pragma unroll
;       for (int i = 0; i < 8; ++i) {
;         const float a = AUa[(8 * ssg + i) * 33 + sc], uu = AUu[(8 * ssg + i) * 33 + sc];
;         Hh = a * Hh + uu; A *= a;
;       }
;       SEGA[ssg * 32 + sc] = A; SEGH[ssg * 32 + sc] = Hh;
;     }
;     __syncthreads();
;     float hin = CARRY[sc];
; #pragma unroll
;     for (int s2 = 0; s2 < 7; ++s2)
;       if (s2 < ssg) hin = SEGA[s2 * 32 + sc] * hin + SEGH[s2 * 32 + sc];
	v_lshlrev_b32_e32 v13, 16, v13
	v_add_u32_e32 v139, 12, v72
	v_mul_f32_e32 v14, v14, v60
	v_mul_f32_e32 v13, v14, v13
	v_add_f32_e32 v14, v4, v56
	v_mul_f32_e32 v14, 0xbfb8aa3b, v14
	v_exp_f32_e32 v14, v14
	ds_write2st64_b32 v139, v15, v13 offset0:136 offset1:169
	ds_read_u16 v13, v113 offset:32
	v_add_f32_e32 v14, 1.0, v14
	v_rcp_f32_e64 v14, -v14
	s_nop 0
	v_mul_f32_e32 v14, v97, v14
	v_mul_f32_e32 v15, 0x3fb8aa3b, v14
	v_exp_f32_e32 v15, v15
	v_add_f32_e32 v14, v14, v14
	v_cmp_nlt_f32_e64 s[52:53], s29, v14
	s_and_saveexec_b64 s[4:5], s[52:53]
	s_xor_b64 s[4:5], exec, s[4:5]
	v_fma_f32 v56, -v15, v15, 1.0
	s_andn2_saveexec_b64 s[4:5], s[4:5]
	v_pk_mul_f32 v[60:61], v[14:15], s[88:89] op_sel_hi:[0,1]
	v_add_f32_e32 v56, 1.0, v61
	v_fma_f32 v56, v60, v56, 1.0
	v_mul_f32_e64 v56, v56, -v14
	s_or_b64 exec, exec, s[4:5]
	v_add_f32_e32 v14, v16, v52
	v_mul_f32_e32 v14, 0xbfb8aa3b, v14
	v_exp_f32_e32 v14, v14
	v_max_f32_e32 v52, v56, v56
	v_max_f32_e32 v52, 0, v52
	v_sqrt_f32_e32 v52, v52
	v_add_f32_e32 v14, 1.0, v14
	v_rcp_f32_e32 v14, v14
	s_waitcnt lgkmcnt(0)
	v_lshlrev_b32_e32 v13, 16, v13
	v_add_u32_e32 v141, 64, v72
	v_mul_f32_e32 v14, v14, v52
	v_mul_f32_e32 v13, v14, v13
	v_add_f32_e32 v14, v5, v57
	v_mul_f32_e32 v14, 0xbfb8aa3b, v14
	v_exp_f32_e32 v14, v14
	ds_write2st64_b32 v141, v15, v13 offset0:136 offset1:169
	ds_read_u16 v13, v113 offset:34
	v_add_f32_e32 v14, 1.0, v14
	v_rcp_f32_e64 v14, -v14
	s_nop 0
	v_mul_f32_e32 v14, v98, v14
	v_mul_f32_e32 v15, 0x3fb8aa3b, v14
	v_exp_f32_e32 v15, v15
	v_add_f32_e32 v14, v14, v14
	v_cmp_nlt_f32_e64 s[52:53], s29, v14
	s_and_saveexec_b64 s[4:5], s[52:53]
	s_xor_b64 s[4:5], exec, s[4:5]
	v_fma_f32 v52, -v15, v15, 1.0
	s_andn2_saveexec_b64 s[4:5], s[4:5]
	v_pk_mul_f32 v[56:57], v[14:15], s[88:89] op_sel_hi:[0,1]
	v_add_f32_e32 v52, 1.0, v57
	v_fma_f32 v52, v56, v52, 1.0
	v_mul_f32_e64 v52, v52, -v14
	s_or_b64 exec, exec, s[4:5]
	v_add_f32_e32 v14, v17, v53
	v_mul_f32_e32 v14, 0xbfb8aa3b, v14
	v_exp_f32_e32 v14, v14
	v_max_f32_e32 v52, v52, v52
	v_max_f32_e32 v52, 0, v52
	v_sqrt_f32_e32 v52, v52
	v_add_f32_e32 v14, 1.0, v14
	v_rcp_f32_e32 v14, v14
	s_waitcnt lgkmcnt(0)
	v_lshlrev_b32_e32 v13, 16, v13
	v_add_u32_e32 v142, 0x44, v72
	v_mul_f32_e32 v14, v14, v52
	v_mul_f32_e32 v13, v14, v13
	v_add_f32_e32 v14, v6, v58
	v_mul_f32_e32 v14, 0xbfb8aa3b, v14
	v_exp_f32_e32 v14, v14
	ds_write2st64_b32 v142, v15, v13 offset0:136 offset1:169
	ds_read_u16 v13, v113 offset:36
	v_add_f32_e32 v14, 1.0, v14
	v_rcp_f32_e64 v14, -v14
	s_nop 0
	v_mul_f32_e32 v14, v99, v14
	v_mul_f32_e32 v15, 0x3fb8aa3b, v14
	v_exp_f32_e32 v15, v15
	v_add_f32_e32 v14, v14, v14
	v_cmp_nlt_f32_e64 s[52:53], s29, v14
	s_and_saveexec_b64 s[4:5], s[52:53]
	s_xor_b64 s[4:5], exec, s[4:5]
	v_fma_f32 v52, -v15, v15, 1.0
	s_andn2_saveexec_b64 s[4:5], s[4:5]
	v_pk_mul_f32 v[52:53], v[14:15], s[88:89] op_sel_hi:[0,1]
	v_add_f32_e32 v53, 1.0, v53
	v_fma_f32 v52, v52, v53, 1.0
	v_mul_f32_e64 v52, v52, -v14
	s_or_b64 exec, exec, s[4:5]
	v_add_f32_e32 v14, v18, v54
	v_mul_f32_e32 v14, 0xbfb8aa3b, v14
	v_exp_f32_e32 v14, v14
	v_max_f32_e32 v52, v52, v52
	v_max_f32_e32 v52, 0, v52
	v_sqrt_f32_e32 v52, v52
	v_add_f32_e32 v14, 1.0, v14
	v_rcp_f32_e32 v14, v14
	s_waitcnt lgkmcnt(0)
	v_lshlrev_b32_e32 v13, 16, v13
	v_add_u32_e32 v144, 0x48, v72
	v_mul_f32_e32 v14, v14, v52
	v_mul_f32_e32 v13, v14, v13
	v_add_f32_e32 v14, v7, v59
	v_mul_f32_e32 v14, 0xbfb8aa3b, v14
	v_exp_f32_e32 v14, v14
	ds_write2st64_b32 v144, v15, v13 offset0:136 offset1:169
	ds_read_u16 v13, v113 offset:38
	v_add_f32_e32 v14, 1.0, v14
	v_rcp_f32_e64 v14, -v14
	s_nop 0
	v_mul_f32_e32 v14, v105, v14
	v_mul_f32_e32 v15, 0x3fb8aa3b, v14
	v_exp_f32_e32 v15, v15
	v_add_f32_e32 v14, v14, v14
	v_cmp_nlt_f32_e64 s[52:53], s29, v14
	s_and_saveexec_b64 s[4:5], s[52:53]
	s_xor_b64 s[4:5], exec, s[4:5]
	v_fma_f32 v52, -v15, v15, 1.0
	s_andn2_saveexec_b64 s[4:5], s[4:5]
	v_pk_mul_f32 v[52:53], v[14:15], s[88:89] op_sel_hi:[0,1]
	v_add_f32_e32 v53, 1.0, v53
	v_fma_f32 v52, v52, v53, 1.0
	v_mul_f32_e64 v52, v52, -v14
	s_or_b64 exec, exec, s[4:5]
	v_add_f32_e32 v14, v19, v55
	v_mul_f32_e32 v14, 0xbfb8aa3b, v14
	v_exp_f32_e32 v14, v14
	v_max_f32_e32 v52, v52, v52
	v_max_f32_e32 v52, 0, v52
	v_sqrt_f32_e32 v52, v52
	v_add_f32_e32 v14, 1.0, v14
	v_rcp_f32_e32 v14, v14
	s_waitcnt lgkmcnt(0)
	v_lshlrev_b32_e32 v13, 16, v13
	v_add_u32_e32 v145, 0x4c, v72
	v_add_u32_e32 v137, 0x8800, v114
	v_mul_f32_e32 v14, v14, v52
	v_mul_f32_e32 v13, v14, v13
	v_add_u32_e32 v138, 0xa800, v114
	ds_write2st64_b32 v145, v15, v13 offset0:136 offset1:169
	s_waitcnt lgkmcnt(0)
	s_barrier
	ds_read2_b32 v[14:15], v137 offset1:33
	ds_read2_b32 v[52:53], v138 offset0:64 offset1:97
	v_add_u32_e32 v140, 0xac00, v114
	s_waitcnt lgkmcnt(0)
	v_fma_f32 v13, 0, v14, v52
	v_fmac_f32_e32 v53, v13, v15
	v_mul_f32_e32 v13, v14, v15
	ds_read2_b32 v[14:15], v137 offset0:66 offset1:99
	ds_read2_b32 v[54:55], v138 offset0:130 offset1:163
	s_waitcnt lgkmcnt(1)
	v_mul_f32_e32 v13, v13, v14
	s_waitcnt lgkmcnt(0)
	v_fma_f32 v52, v53, v14, v54
	v_fmac_f32_e32 v55, v52, v15
	v_mul_f32_e32 v13, v13, v15
	ds_read2_b32 v[14:15], v137 offset0:132 offset1:165
	ds_read2_b32 v[52:53], v138 offset0:196 offset1:229
	s_waitcnt lgkmcnt(1)
	v_mul_f32_e32 v13, v13, v14
	s_waitcnt lgkmcnt(0)
	v_fma_f32 v52, v55, v14, v52
	v_fmac_f32_e32 v53, v52, v15
	v_mul_f32_e32 v13, v13, v15
	ds_read2_b32 v[14:15], v137 offset0:198 offset1:231
	ds_read2_b32 v[54:55], v140 offset0:6 offset1:39
	s_waitcnt lgkmcnt(1)
	v_mul_f32_e32 v13, v13, v14
	s_waitcnt lgkmcnt(0)
	v_fma_f32 v52, v53, v14, v54
	v_fmac_f32_e32 v55, v52, v15
	v_mul_f32_e32 v13, v13, v15
	ds_write2st64_b32 v78, v13, v55 offset0:202 offset1:206
	s_waitcnt lgkmcnt(0)
	s_barrier
	ds_read_b32 v13, v115 offset:53760
	s_and_saveexec_b64 s[4:5], vcc
	s_cbranch_execz .LBB0_1548
	ds_read2st64_b32 v[14:15], v115 offset0:202 offset1:206
	s_waitcnt lgkmcnt(0)
	v_fmac_f32_e32 v15, v13, v14
	v_mov_b32_e32 v13, v15
	s_or_b64 exec, exec, s[4:5]
	v_add_u32_e32 v143, 0x80, v115
	s_and_saveexec_b64 s[4:5], s[38:39]
	s_cbranch_execnz .LBB0_1549

; #define MFMA16(a, b, c) __builtin_amdgcn_mfma_f32_16x16x32_bf16((a), (b), (c), 0, 0, 0)
; __device__ __forceinline__ void rglru_unit(const Params& p, const WS& ws, int j, int u, bool dry = false) {
;     ...
;   auto prefetch = [&](int tile, u32x4 (&xin)[4], bf16_t (&gav)[8]) {
;     const int t0 = 64 * tile;
; #pragma unroll
;     for (int i = 0; i < 4; ++i) {
;       const int ci = tid + 256 * i; const int row = ci >> 4, ch = ci & 15; const int t = t0 + row;
;       xin[i] = (u32x4){0, 0, 0, 0};
;       if (t < T_) xin[i] = *(const u32x4*)(ws.XA + (size_t)(b * T_ + t) * 1024 + 128 * g + 8 * ch);
;     }
; #pragma unroll
;     for (int i = 0; i < 8; ++i) {
;       const int t = t0 + 8 * ssg + i;
;       gav[i] = 0;
;       if (t < T_) gav[i] = ws.GA[(size_t)(b * T_ + t) * 1024 + 128 * g + 32 * jq + sc];
;     }
;     ...
;       for (int ks = 0; ks < 4; ++ks) {
;         const bf16x8 xf = *(const bf16x8*)(XC + (16 * w + lr) * 136 + 32 * ks + 8 * lq);
; #pragma unroll
;         for (int gate = 0; gate < 2; ++gate)
; #pragma unroll
;           for (int mt = 0; mt < 2; ++mt) {
;             const bf16x8 wf = *(const bf16x8*)(WG + (gate * 32 + 16 * mt + lr) * 136 + 32 * ks + 8 * lq);
;             ga_[gate][mt] = MFMA16(wf, xf, ga_[gate][mt]);
;           }
;       }
.Lrg_g2_skip:
	s_cmp_gt_u32 s7, 30
	v_mov_b32_e32 v151, v94
	v_mov_b32_e32 v152, v92
	v_mov_b32_e32 v149, v90
	v_mov_b32_e32 v150, v91
	v_mov_b32_e32 v147, v87
	v_mov_b32_e32 v243, v86
	v_mov_b32_e32 v146, v85
	v_mov_b32_e32 v148, v88
	s_cbranch_scc1 .LBB0_1505
	s_cmpk_gt_i32 s6, 0x710
	s_cbranch_scc1 .Lrg_pslow2
	ds_read_b128 v[52:55], v111
	ds_read_b128 v[56:59], v112 offset:17408
	ds_read_b128 v[60:63], v112 offset:21760
	ds_read_b128 v[64:67], v112 offset:26112
	ds_read_b128 v[120:123], v112 offset:30464
	ds_read_b128 v[212:215], v111 offset:64
	ds_read_b128 v[216:219], v111 offset:128
	ds_read_b128 v[220:223], v111 offset:192
	ds_read_b128 v[224:227], v112 offset:17472
	ds_read_b128 v[228:231], v112 offset:21824
	ds_read_b128 v[232:235], v112 offset:26176
	ds_read_b128 v[244:247], v112 offset:30528
	ds_read_b128 v[248:251], v112 offset:17536
	ds_read_b128 v[252:255], v112 offset:21888
	s_mov_b64 s[4:5], 0x1000
	s_mov_b64 s[52:53], 0x8000
	v_add_u32_e32 v14, s6, v118
	v_add_u32_e32 v14, 0xc0, v14
	v_ashrrev_i32_e32 v15, 31, v14
	v_lshlrev_b64 v[14:15], 11, v[14:15]
	v_lshl_add_u64 v[14:15], v[76:77], 0, v[14:15]
	global_load_dwordx4 v[36:39], v[14:15], off
	v_lshl_add_u64 v[14:15], v[14:15], 0, s[52:53]
	global_load_dwordx4 v[40:43], v[14:15], off
	v_lshl_add_u64 v[14:15], v[14:15], 0, s[52:53]
	global_load_dwordx4 v[44:47], v[14:15], off
	v_lshl_add_u64 v[14:15], v[14:15], 0, s[52:53]
	global_load_dwordx4 v[48:51], v[14:15], off
	v_add_u32_e32 v14, s6, v69
	v_add_u32_e32 v14, 0xc0, v14
	v_ashrrev_i32_e32 v15, 31, v14
	v_lshlrev_b64 v[14:15], 11, v[14:15]
	v_lshl_add_u64 v[14:15], v[74:75], 0, v[14:15]
	global_load_ushort v243, v[14:15], off
	global_load_ushort v146, v[14:15], off offset:2048
	v_lshl_add_u64 v[14:15], v[14:15], 0, s[4:5]
	global_load_ushort v148, v[14:15], off
	global_load_ushort v147, v[14:15], off offset:2048
	v_lshl_add_u64 v[14:15], v[14:15], 0, s[4:5]
	global_load_ushort v150, v[14:15], off
	global_load_ushort v149, v[14:15], off offset:2048
	v_lshl_add_u64 v[14:15], v[14:15], 0, s[4:5]
	global_load_ushort v152, v[14:15], off
	global_load_ushort v151, v[14:15], off offset:2048
	s_branch .Lrg_mm2

; __device__ __forceinline__ float bf2f(bf16_t v) { return __uint_as_float(((unsigned)v) << 16); }
; __device__ __forceinline__ float sigmoidf_(float x) { return __builtin_amdgcn_rcpf(1.f + __expf(-x)); }
; #define MFMA16(a, b, c) __builtin_amdgcn_mfma_f32_16x16x32_bf16((a), (b), (c), 0, 0, 0)
; __device__ __forceinline__ void rglru_unit(const Params& p, const WS& ws, int j, int u, bool dry = false) {
;     ...
;       for (int ks = 0; ks < 4; ++ks) {
;         const bf16x8 xf = *(const bf16x8*)(XC + (16 * w + lr) * 136 + 32 * ks + 8 * lq);
; #pragma unroll
;         for (int gate = 0; gate < 2; ++gate)
; #pragma unroll
;           for (int mt = 0; mt < 2; ++mt) {
;             const bf16x8 wf = *(const bf16x8*)(WG + (gate * 32 + 16 * mt + lr) * 136 + 32 * ks + 8 * lq);
;             ga_[gate][mt] = MFMA16(wf, xf, ga_[gate][mt]);
;           }
;       }
;       const int tok = 16 * w + lr;
; #pragma unroll
;       for (int mt = 0; mt < 2; ++mt)
; #pragma unroll
;         for (int jj = 0; jj < 4; ++jj) {
;           const int n = 16 * mt + 4 * lq + jj;
;           const float xcv = bf2f(XC[tok * 136 + 32 * jq + n]);
;           const float r = sigmoidf_(ga_[0][mt][jj] + ba[mt][jj]);
;           const float ig = sigmoidf_(ga_[1][mt][jj] + bx[mt][jj]);
;           const float la = -r * sp[mt][jj];
;           const float a = __expf(la);
;           const float x2 = 2.f * la;
;           const float om = x2 > -0.02f ? -x2 * (1.f + 0.5f * x2 * (1.f + x2 * (1.f / 3.f))) : 1.f - a * a;
;           const float mult = __builtin_amdgcn_sqrtf(fmaxf(om, 0.f));
;           AUa[tok * 33 + n] = a;
;           AUu[tok * 33 + n] = mult * ig * xcv;
;         }
.Lrg_mm2:
	s_waitcnt lgkmcnt(12)
	v_mfma_f32_16x16x32_bf16 v[56:59], v[56:59], v[52:55], 0
	s_waitcnt lgkmcnt(11)
	v_mfma_f32_16x16x32_bf16 v[60:63], v[60:63], v[52:55], 0
	s_waitcnt lgkmcnt(10)
	v_mfma_f32_16x16x32_bf16 v[64:67], v[64:67], v[52:55], 0
	s_waitcnt lgkmcnt(9)
	v_mfma_f32_16x16x32_bf16 v[52:55], v[120:123], v[52:55], 0
	s_nop 0
	s_nop 0
	s_waitcnt lgkmcnt(5)
	v_mfma_f32_16x16x32_bf16 v[56:59], v[224:227], v[212:215], v[56:59]
	ds_read_b128 v[224:227], v112 offset:26240
	s_nop 0
	s_waitcnt lgkmcnt(5)
	v_mfma_f32_16x16x32_bf16 v[60:63], v[228:231], v[212:215], v[60:63]
	ds_read_b128 v[228:231], v112 offset:30592
	s_nop 0
	s_waitcnt lgkmcnt(5)
	v_mfma_f32_16x16x32_bf16 v[64:67], v[232:235], v[212:215], v[64:67]
	ds_read_b128 v[232:235], v112 offset:17600
	s_nop 0
	s_waitcnt lgkmcnt(5)
	v_mfma_f32_16x16x32_bf16 v[52:55], v[244:247], v[212:215], v[52:55]
	ds_read_b128 v[244:247], v112 offset:21952
	s_nop 0
	s_nop 0
	s_waitcnt lgkmcnt(5)
	v_mfma_f32_16x16x32_bf16 v[56:59], v[248:251], v[216:219], v[56:59]
	ds_read_b128 v[248:251], v112 offset:26304
	s_nop 0
	s_waitcnt lgkmcnt(5)
	v_mfma_f32_16x16x32_bf16 v[60:63], v[252:255], v[216:219], v[60:63]
	ds_read_b128 v[252:255], v112 offset:30656
	s_nop 0
	s_waitcnt lgkmcnt(5)
	v_mfma_f32_16x16x32_bf16 v[154:157], v[224:227], v[216:219], v[64:67]
	s_nop 2
	s_nop 0
	s_waitcnt lgkmcnt(4)
	v_mfma_f32_16x16x32_bf16 v[52:55], v[228:231], v[216:219], v[52:55]
	s_nop 0
	s_nop 0
	ds_read_u16 v15, v113
	s_waitcnt lgkmcnt(4)
	v_mfma_f32_16x16x32_bf16 v[64:67], v[232:235], v[220:223], v[56:59]
	s_nop 2
	s_nop 0
	s_waitcnt lgkmcnt(3)
	v_mfma_f32_16x16x32_bf16 v[56:59], v[244:247], v[220:223], v[60:63]
	s_nop 2
	s_nop 0
	v_add_f32_e32 v14, v0, v64
	v_mul_f32_e32 v14, 0xbfb8aa3b, v14
	v_exp_f32_e32 v14, v14
	s_waitcnt lgkmcnt(2)
	v_mfma_f32_16x16x32_bf16 v[60:63], v[248:251], v[220:223], v[154:157]
	s_nop 2
	s_nop 0
	v_add_f32_e32 v14, 1.0, v14
	v_rcp_f32_e64 v14, -v14
	s_waitcnt lgkmcnt(0)
	v_mfma_f32_16x16x32_bf16 v[52:55], v[252:255], v[220:223], v[52:55]
	v_mul_f32_e32 v14, v89, v14
	v_mul_f32_e32 v64, 0x3fb8aa3b, v14
	v_exp_f32_e32 v64, v64
	v_add_f32_e32 v14, v14, v14
	v_cmp_nlt_f32_e64 s[52:53], s29, v14
	s_and_saveexec_b64 s[4:5], s[52:53]
	s_xor_b64 s[4:5], exec, s[4:5]
	v_fma_f32 v119, -v64, v64, 1.0
	s_andn2_saveexec_b64 s[4:5], s[4:5]
	v_pk_mul_f32 v[120:121], v[14:15], s[88:89] op_sel_hi:[0,1]
	v_add_f32_e32 v119, 1.0, v121
	v_fma_f32 v119, v120, v119, 1.0
	v_mul_f32_e64 v119, v119, -v14
	s_or_b64 exec, exec, s[4:5]
	v_add_f32_e32 v14, v8, v60
	v_add_f32_e32 v65, v1, v65
	v_mul_f32_e32 v14, 0xbfb8aa3b, v14
	v_mul_f32_e32 v65, 0xbfb8aa3b, v65
	v_exp_f32_e32 v14, v14
	v_exp_f32_e32 v65, v65
	v_max_f32_e32 v60, v119, v119
	v_max_f32_e32 v60, 0, v60
	v_add_f32_e32 v14, 1.0, v14
	v_add_f32_e32 v65, 1.0, v65
	v_rcp_f32_e32 v14, v14
	v_sqrt_f32_e32 v60, v60
	v_rcp_f32_e64 v65, -v65
	v_lshlrev_b32_e32 v15, 16, v15
	v_mul_f32_e32 v14, v14, v60
	v_mul_f32_e32 v65, v93, v65
	v_mul_f32_e32 v14, v14, v15
	ds_read_u16 v60, v113 offset:2
	v_mul_f32_e32 v15, 0x3fb8aa3b, v65
	v_exp_f32_e32 v15, v15
	ds_write2st64_b32 v72, v64, v14 offset0:136 offset1:169
	v_add_f32_e32 v14, v65, v65
	v_cmp_nlt_f32_e64 s[52:53], s29, v14
	s_and_saveexec_b64 s[4:5], s[52:53]
	s_xor_b64 s[4:5], exec, s[4:5]
	v_fma_f32 v64, -v15, v15, 1.0
	s_andn2_saveexec_b64 s[4:5], s[4:5]
	v_pk_mul_f32 v[64:65], v[14:15], s[88:89] op_sel_hi:[0,1]
	v_add_f32_e32 v65, 1.0, v65
	v_fma_f32 v64, v64, v65, 1.0
	v_mul_f32_e64 v64, v64, -v14
	s_or_b64 exec, exec, s[4:5]
	v_add_f32_e32 v14, v9, v61
	v_max_f32_e32 v61, v64, v64
	v_add_f32_e32 v64, v2, v66
	v_mul_f32_e32 v14, 0xbfb8aa3b, v14
	v_mul_f32_e32 v64, 0xbfb8aa3b, v64
	v_exp_f32_e32 v14, v14
	v_exp_f32_e32 v64, v64
	v_max_f32_e32 v61, 0, v61
	v_sqrt_f32_e32 v61, v61
	v_add_f32_e32 v14, 1.0, v14
	v_add_f32_e32 v64, 1.0, v64
	v_rcp_f32_e32 v14, v14
	v_rcp_f32_e64 v64, -v64
	s_waitcnt lgkmcnt(1)
	v_lshlrev_b32_e32 v60, 16, v60
	v_mul_f32_e32 v14, v14, v61
	v_mul_f32_e32 v64, v95, v64
	v_mul_f32_e32 v14, v14, v60
	ds_read_u16 v61, v113 offset:4
	v_mul_f32_e32 v60, 0x3fb8aa3b, v64
	v_exp_f32_e32 v60, v60
	ds_write2st64_b32 v135, v15, v14 offset0:136 offset1:169
	v_add_f32_e32 v14, v64, v64
	v_cmp_nlt_f32_e64 s[52:53], s29, v14
	s_and_saveexec_b64 s[4:5], s[52:53]
	s_xor_b64 s[4:5], exec, s[4:5]
	v_fma_f32 v15, -v60, v60, 1.0
	s_andn2_saveexec_b64 s[4:5], s[4:5]
	v_pk_mul_f32 v[64:65], v[14:15], s[88:89] op_sel_hi:[0,1]
	v_add_f32_e32 v15, 1.0, v65
	v_fma_f32 v15, v64, v15, 1.0
	v_mul_f32_e64 v15, v15, -v14
	s_or_b64 exec, exec, s[4:5]
	v_add_f32_e32 v14, v10, v62
	v_add_f32_e32 v62, v3, v67
	v_mul_f32_e32 v14, 0xbfb8aa3b, v14
	v_mul_f32_e32 v62, 0xbfb8aa3b, v62
	v_exp_f32_e32 v14, v14
	v_exp_f32_e32 v62, v62
	v_max_f32_e32 v15, v15, v15
	v_max_f32_e32 v15, 0, v15
	v_add_f32_e32 v14, 1.0, v14
	v_add_f32_e32 v62, 1.0, v62
	v_rcp_f32_e32 v14, v14
	v_sqrt_f32_e32 v15, v15
	v_rcp_f32_e64 v62, -v62
	s_waitcnt lgkmcnt(1)
	v_lshlrev_b32_e32 v61, 16, v61
	v_mul_f32_e32 v14, v14, v15
	v_mul_f32_e32 v62, v96, v62
	v_mul_f32_e32 v14, v14, v61
	ds_read_u16 v61, v113 offset:6
	v_mul_f32_e32 v15, 0x3fb8aa3b, v62
	v_exp_f32_e32 v15, v15
	ds_write2st64_b32 v136, v60, v14 offset0:136 offset1:169
	v_add_f32_e32 v14, v62, v62
	v_cmp_nlt_f32_e64 s[52:53], s29, v14
	s_and_saveexec_b64 s[4:5], s[52:53]
	s_xor_b64 s[4:5], exec, s[4:5]
	v_fma_f32 v60, -v15, v15, 1.0
	s_andn2_saveexec_b64 s[4:5], s[4:5]
	v_pk_mul_f32 v[64:65], v[14:15], s[88:89] op_sel_hi:[0,1]
	v_add_f32_e32 v60, 1.0, v65
	v_fma_f32 v60, v64, v60, 1.0
	v_mul_f32_e64 v60, v60, -v14
	s_or_b64 exec, exec, s[4:5]
	v_add_f32_e32 v14, v11, v63
	v_mul_f32_e32 v14, 0xbfb8aa3b, v14
	v_add_f32_e32 v56, v4, v56
	v_exp_f32_e32 v14, v14
	v_mul_f32_e32 v56, 0xbfb8aa3b, v56
	v_exp_f32_e32 v56, v56
	v_max_f32_e32 v60, v60, v60
	v_add_f32_e32 v14, 1.0, v14
	v_max_f32_e32 v60, 0, v60
	v_rcp_f32_e32 v14, v14
	v_sqrt_f32_e32 v60, v60
	v_add_f32_e32 v56, 1.0, v56
	v_rcp_f32_e64 v56, -v56
	s_waitcnt lgkmcnt(1)
; __device__ __forceinline__ float bf2f(bf16_t v) { return __uint_as_float(((unsigned)v) << 16); }
; __device__ __forceinline__ float sigmoidf_(float x) { return __builtin_amdgcn_rcpf(1.f + __expf(-x)); }
; __device__ __forceinline__ void rglru_unit(const Params& p, const WS& ws, int j, int u, bool dry = false) {
;     ...
; #pragma unroll
;       for (int mt = 0; mt < 2; ++mt)
; #pragma unroll
;         for (int jj = 0; jj < 4; ++jj) {
;           const int n = 16 * mt + 4 * lq + jj;
;           const float xcv = bf2f(XC[tok * 136 + 32 * jq + n]);
;           const float r = sigmoidf_(ga_[0][mt][jj] + ba[mt][jj]);
;           const float ig = sigmoidf_(ga_[1][mt][jj] + bx[mt][jj]);
;           const float la = -r * sp[mt][jj];
;           const float a = __expf(la);
;           const float x2 = 2.f * la;
;           const float om = x2 > -0.02f ? -x2 * (1.f + 0.5f * x2 * (1.f + x2 * (1.f / 3.f))) : 1.f - a * a;
;           const float mult = __builtin_amdgcn_sqrtf(fmaxf(om, 0.f));
;           AUa[tok * 33 + n] = a;
;           AUu[tok * 33 + n] = mult * ig * xcv;
;         }
;     }
;     __syncthreads();
;     {
;       float A = 1.f, Hh = 0.f;
; #pragma unroll
;       for (int i = 0; i < 8; ++i) {
;         const float a = AUa[(8 * ssg + i) * 33 + sc], uu = AUu[(8 * ssg + i) * 33 + sc];
;         Hh = a * Hh + uu; A *= a;
;       }
;       SEGA[ssg * 32 + sc] = A; SEGH[ssg * 32 + sc] = Hh;
;     }
;     __syncthreads();
;     float hin = CARRY[sc];
; #pragma unroll
;     for (int s2 = 0; s2 < 7; ++s2)
;       if (s2 < ssg) hin = SEGA[s2 * 32 + sc] * hin + SEGH[s2 * 32 + sc];
	v_lshlrev_b32_e32 v61, 16, v61
	v_mul_f32_e32 v14, v14, v60
	v_mul_f32_e32 v14, v14, v61
	v_mul_f32_e32 v61, v97, v56
	ds_read_u16 v60, v113 offset:32
	v_mul_f32_e32 v56, 0x3fb8aa3b, v61
	v_exp_f32_e32 v56, v56
	ds_write2st64_b32 v139, v15, v14 offset0:136 offset1:169
	v_add_f32_e32 v14, v61, v61
	v_cmp_nlt_f32_e64 s[52:53], s29, v14
	s_and_saveexec_b64 s[4:5], s[52:53]
	s_xor_b64 s[4:5], exec, s[4:5]
	v_fma_f32 v15, -v56, v56, 1.0
	s_andn2_saveexec_b64 s[4:5], s[4:5]
	v_pk_mul_f32 v[62:63], v[14:15], s[88:89] op_sel_hi:[0,1]
	v_add_f32_e32 v15, 1.0, v63
	v_fma_f32 v15, v62, v15, 1.0
	v_mul_f32_e64 v15, v15, -v14
	s_or_b64 exec, exec, s[4:5]
	v_add_f32_e32 v14, v16, v52
	v_mul_f32_e32 v14, 0xbfb8aa3b, v14
	v_add_f32_e32 v52, v5, v57
	v_exp_f32_e32 v14, v14
	v_mul_f32_e32 v52, 0xbfb8aa3b, v52
	v_exp_f32_e32 v52, v52
	v_max_f32_e32 v15, v15, v15
	v_add_f32_e32 v14, 1.0, v14
	v_max_f32_e32 v15, 0, v15
	v_rcp_f32_e32 v14, v14
	v_sqrt_f32_e32 v15, v15
	v_add_f32_e32 v52, 1.0, v52
	s_waitcnt lgkmcnt(1)
	v_lshlrev_b32_e32 v57, 16, v60
	v_rcp_f32_e64 v60, -v52
	v_mul_f32_e32 v14, v14, v15
	v_mul_f32_e32 v14, v14, v57
	ds_read_u16 v52, v113 offset:34
	v_mul_f32_e32 v57, v98, v60
	v_mul_f32_e32 v15, 0x3fb8aa3b, v57
	v_exp_f32_e32 v15, v15
	ds_write2st64_b32 v141, v56, v14 offset0:136 offset1:169
	v_add_f32_e32 v14, v57, v57
	v_cmp_nlt_f32_e64 s[52:53], s29, v14
	s_and_saveexec_b64 s[4:5], s[52:53]
	s_xor_b64 s[4:5], exec, s[4:5]
	v_fma_f32 v56, -v15, v15, 1.0
	s_andn2_saveexec_b64 s[4:5], s[4:5]
	v_pk_mul_f32 v[56:57], v[14:15], s[88:89] op_sel_hi:[0,1]
	v_add_f32_e32 v57, 1.0, v57
	v_fma_f32 v56, v56, v57, 1.0
	v_mul_f32_e64 v56, v56, -v14
	s_or_b64 exec, exec, s[4:5]
	v_add_f32_e32 v14, v17, v53
	v_max_f32_e32 v53, v56, v56
	v_add_f32_e32 v56, v6, v58
	v_mul_f32_e32 v14, 0xbfb8aa3b, v14
	v_mul_f32_e32 v56, 0xbfb8aa3b, v56
	v_exp_f32_e32 v14, v14
	v_exp_f32_e32 v56, v56
	v_max_f32_e32 v53, 0, v53
	v_sqrt_f32_e32 v53, v53
	v_add_f32_e32 v14, 1.0, v14
	v_add_f32_e32 v56, 1.0, v56
	v_rcp_f32_e32 v14, v14
	v_rcp_f32_e64 v56, -v56
	s_waitcnt lgkmcnt(1)
	v_lshlrev_b32_e32 v52, 16, v52
	v_mul_f32_e32 v14, v14, v53
	v_mul_f32_e32 v56, v99, v56
	v_mul_f32_e32 v14, v14, v52
	ds_read_u16 v53, v113 offset:36
	v_mul_f32_e32 v52, 0x3fb8aa3b, v56
	v_exp_f32_e32 v52, v52
	ds_write2st64_b32 v142, v15, v14 offset0:136 offset1:169
	v_add_f32_e32 v14, v56, v56
	v_cmp_nlt_f32_e64 s[52:53], s29, v14
	s_and_saveexec_b64 s[4:5], s[52:53]
	s_xor_b64 s[4:5], exec, s[4:5]
	v_fma_f32 v15, -v52, v52, 1.0
	s_andn2_saveexec_b64 s[4:5], s[4:5]
	v_pk_mul_f32 v[56:57], v[14:15], s[88:89] op_sel_hi:[0,1]
	v_add_f32_e32 v15, 1.0, v57
	v_fma_f32 v15, v56, v15, 1.0
	v_mul_f32_e64 v15, v15, -v14
	s_or_b64 exec, exec, s[4:5]
	v_add_f32_e32 v14, v18, v54
	v_add_f32_e32 v54, v7, v59
	v_mul_f32_e32 v14, 0xbfb8aa3b, v14
	v_mul_f32_e32 v54, 0xbfb8aa3b, v54
	v_exp_f32_e32 v14, v14
	v_exp_f32_e32 v54, v54
	v_max_f32_e32 v15, v15, v15
	v_max_f32_e32 v15, 0, v15
	v_add_f32_e32 v14, 1.0, v14
	v_add_f32_e32 v54, 1.0, v54
	v_rcp_f32_e32 v14, v14
	v_sqrt_f32_e32 v15, v15
	v_rcp_f32_e64 v54, -v54
	s_waitcnt lgkmcnt(1)
	v_lshlrev_b32_e32 v53, 16, v53
	v_mul_f32_e32 v14, v14, v15
	v_mul_f32_e32 v54, v105, v54
	v_mul_f32_e32 v14, v14, v53
	ds_read_u16 v53, v113 offset:38
	v_mul_f32_e32 v15, 0x3fb8aa3b, v54
	v_exp_f32_e32 v15, v15
	ds_write2st64_b32 v144, v52, v14 offset0:136 offset1:169
	v_add_f32_e32 v14, v54, v54
	v_cmp_nlt_f32_e64 s[52:53], s29, v14
	s_and_saveexec_b64 s[4:5], s[52:53]
	s_xor_b64 s[4:5], exec, s[4:5]
	v_fma_f32 v52, -v15, v15, 1.0
	s_andn2_saveexec_b64 s[4:5], s[4:5]
	v_pk_mul_f32 v[56:57], v[14:15], s[88:89] op_sel_hi:[0,1]
	v_add_f32_e32 v52, 1.0, v57
	v_fma_f32 v52, v56, v52, 1.0
	v_mul_f32_e64 v52, v52, -v14
	s_or_b64 exec, exec, s[4:5]
	s_waitcnt lgkmcnt(1)
	v_lshlrev_b32_e32 v14, 16, v53
	v_add_f32_e32 v53, v19, v55
	v_mul_f32_e32 v53, 0xbfb8aa3b, v53
	v_exp_f32_e32 v53, v53
	v_max_f32_e32 v52, v52, v52
	v_max_f32_e32 v52, 0, v52
	v_sqrt_f32_e32 v52, v52
	v_add_f32_e32 v53, 1.0, v53
	v_rcp_f32_e32 v53, v53
	s_nop 0
	v_mul_f32_e32 v52, v53, v52
	v_mul_f32_e32 v14, v52, v14
	ds_write2st64_b32 v145, v15, v14 offset0:136 offset1:169
	s_waitcnt lgkmcnt(0)
	s_barrier
	ds_read2_b32 v[14:15], v137 offset1:33
	ds_read2_b32 v[52:53], v138 offset0:64 offset1:97
	s_waitcnt lgkmcnt(0)
	v_fma_f32 v52, 0, v14, v52
	v_fmac_f32_e32 v53, v52, v15
	v_mul_f32_e32 v52, v14, v15
	ds_read2_b32 v[14:15], v137 offset0:66 offset1:99
	ds_read2_b32 v[54:55], v138 offset0:130 offset1:163
	s_waitcnt lgkmcnt(0)
	v_fma_f32 v53, v53, v14, v54
	v_mul_f32_e32 v14, v52, v14
	v_fmac_f32_e32 v55, v53, v15
	v_mul_f32_e32 v54, v14, v15
	ds_read2_b32 v[14:15], v137 offset0:132 offset1:165
	ds_read2_b32 v[52:53], v138 offset0:196 offset1:229
	s_waitcnt lgkmcnt(0)
	v_fma_f32 v52, v55, v14, v52
	v_mul_f32_e32 v14, v54, v14
	v_fmac_f32_e32 v53, v52, v15
	v_mul_f32_e32 v52, v14, v15
	ds_read2_b32 v[14:15], v137 offset0:198 offset1:231
	ds_read2_b32 v[54:55], v140 offset0:6 offset1:39
	s_waitcnt lgkmcnt(0)
	v_fma_f32 v53, v53, v14, v54
	v_mul_f32_e32 v14, v52, v14
	v_fmac_f32_e32 v55, v53, v15
	v_mul_f32_e32 v14, v14, v15
	ds_write2st64_b32 v78, v14, v55 offset0:202 offset1:206
	s_waitcnt lgkmcnt(0)
	s_barrier
	ds_read_b32 v14, v115 offset:53760
	s_and_saveexec_b64 s[4:5], vcc
	s_cbranch_execz .LBB0_1557
	ds_read2st64_b32 v[52:53], v115 offset0:202 offset1:206
	s_waitcnt lgkmcnt(0)
	v_fmac_f32_e32 v53, v14, v52
	v_mov_b32_e32 v14, v53
	s_or_b64 exec, exec, s[4:5]
	s_and_saveexec_b64 s[4:5], s[38:39]
	s_cbranch_execnz .LBB0_1558
